# batched loads in pool_prep d-loop, final_rows and xb_rows (were one load + vmcnt(0) per chunk)
# speedup vs baseline: 1.0433x; 1.0139x over previous
; __device__ __forceinline__ void final_rows(float* X, const float* gvec, const float* ssq, int nrows, int gw, int ngw, int lane) {
;     for (int row = gw; row < nrows; row += ngw) { const float r = rsqrtf(ssq[row] * (1.f / DM) + EPS);
;         f32x4* xr = (f32x4*)(X + (size_t)row * DM) + lane;
; #pragma unroll
;         for (int j = 0; j < 8; ++j) xr[64 * j] = xr[64 * j] * r * ((const f32x4*)gvec)[lane + 64 * j]; }
; }
.LBB0_637:
	s_and_b64 vcc, exec, s[2:3]
	s_cbranch_vccz .LBB0_1306
	v_readlane_b32 s0, v254, 27
	v_readlane_b32 s1, v254, 28
	s_load_dwordx4 s[28:31], s[0:1], 0xb8
	s_ashr_i32 s0, s57, 6
	v_readlane_b32 s1, v253, 4
	s_add_i32 s4, s0, s1
	v_and_b32_e32 v196, 63, v194
	s_waitcnt lgkmcnt(0)
	s_add_u32 s36, s30, 0x15e00000
	s_addc_u32 s37, s31, 0
	s_cmp_lt_i32 s46, 5
	s_mov_b64 s[2:3], -1
	s_cbranch_scc1 .LBB0_857
	s_cmp_lt_i32 s46, 19
	s_cbranch_scc1 .LBB0_827
	s_cmp_lt_i32 s46, 25
	s_cbranch_scc1 .LBB0_646
	s_cmp_eq_u32 s46, 25
	s_cbranch_scc0 .LBB0_645
	s_cmpk_gt_i32 s4, 0x3fff
	s_cbranch_scc1 .LBB0_645
	v_readlane_b32 s0, v254, 27
	v_readlane_b32 s1, v254, 28
	s_load_dwordx2 s[0:1], s[0:1], 0xb0
	v_lshlrev_b32_e32 v12, 4, v196
	v_mov_b32_e32 v13, v0
	s_ashr_i32 s5, s4, 31
	s_mov_b64 s[2:3], 0x1000
	s_waitcnt lgkmcnt(0)
	v_lshl_add_u64 v[2:3], s[0:1], 0, v[12:13]
	s_mov_b64 s[0:1], 0x1400
	v_lshl_add_u64 v[6:7], v[2:3], 0, s[0:1]
	s_mov_b64 s[0:1], 0x1800
	v_lshl_add_u64 v[8:9], v[2:3], 0, s[0:1]
	s_mov_b64 s[0:1], 0x1c00
	v_lshl_add_u64 v[10:11], v[2:3], 0, s[0:1]
	s_lshl_b64 s[0:1], s[4:5], 2
	s_add_u32 s0, s30, s0
	s_addc_u32 s1, s31, s1
	s_add_u32 s6, s0, 0x80000
	s_addc_u32 s7, s1, 0
	s_lshl_b64 s[0:1], s[4:5], 13
	s_add_u32 s0, s28, s0
	s_addc_u32 s1, s29, s1
	v_lshl_add_u64 v[12:13], s[0:1], 0, v[12:13]
	v_lshl_add_u64 v[4:5], v[2:3], 0, s[2:3]
	v_lshl_add_u64 v[12:13], v[12:13], 0, s[2:3]
	v_readlane_b32 s2, v253, 49
	s_mov_b32 s0, s4
	v_readlane_b32 s3, v253, 50
	global_load_dwordx4 v[56:59], v[2:3], off
	global_load_dwordx4 v[60:63], v[2:3], off offset:1024
	global_load_dwordx4 v[64:67], v[2:3], off offset:2048
	global_load_dwordx4 v[68:71], v[2:3], off offset:3072
	global_load_dwordx4 v[72:75], v[4:5], off
	global_load_dwordx4 v[76:79], v[6:7], off
	global_load_dwordx4 v[80:83], v[8:9], off
	global_load_dwordx4 v[84:87], v[10:11], off
.LBB0_644:
	global_load_dword v1, v0, s[6:7]
	global_load_dwordx4 v[24:27], v[12:13], off offset:-4096
	global_load_dwordx4 v[28:31], v[12:13], off offset:-3072
	global_load_dwordx4 v[32:35], v[12:13], off offset:-2048
	global_load_dwordx4 v[36:39], v[12:13], off offset:-1024
	global_load_dwordx4 v[40:43], v[12:13], off
	global_load_dwordx4 v[44:47], v[12:13], off offset:1024
	global_load_dwordx4 v[48:51], v[12:13], off offset:2048
	global_load_dwordx4 v[52:55], v[12:13], off offset:3072
	s_add_u32 s6, s6, s2
	s_addc_u32 s7, s7, s3
	s_waitcnt vmcnt(8)
	v_fmamk_f32 v1, v1, 0x3a000000, v203
	v_cmp_gt_f32_e32 vcc, s80, v1
	v_mul_f32_e32 v14, 0x4b800000, v1
	s_nop 0
	v_cndmask_b32_e32 v1, v1, v14, vcc
	v_rsq_f32_e32 v1, v1
	s_nop 0
	v_mul_f32_e32 v14, 0x45800000, v1
	v_cndmask_b32_e32 v14, v1, v14, vcc
	s_waitcnt vmcnt(7)
	v_pk_mul_f32 v[24:25], v[24:25], v[14:15] op_sel_hi:[1,0]
	v_pk_mul_f32 v[26:27], v[26:27], v[14:15] op_sel_hi:[1,0]
	v_pk_mul_f32 v[24:25], v[24:25], v[56:57]
	v_pk_mul_f32 v[26:27], v[26:27], v[58:59]
	global_store_dwordx4 v[12:13], v[24:27], off offset:-4096
	s_waitcnt vmcnt(7)
	v_pk_mul_f32 v[28:29], v[28:29], v[14:15] op_sel_hi:[1,0]
	v_pk_mul_f32 v[30:31], v[30:31], v[14:15] op_sel_hi:[1,0]
	v_pk_mul_f32 v[28:29], v[28:29], v[60:61]
	v_pk_mul_f32 v[30:31], v[30:31], v[62:63]
	global_store_dwordx4 v[12:13], v[28:31], off offset:-3072
	s_waitcnt vmcnt(7)
	v_pk_mul_f32 v[32:33], v[32:33], v[14:15] op_sel_hi:[1,0]
	v_pk_mul_f32 v[34:35], v[34:35], v[14:15] op_sel_hi:[1,0]
	v_pk_mul_f32 v[32:33], v[32:33], v[64:65]
	v_pk_mul_f32 v[34:35], v[34:35], v[66:67]
	global_store_dwordx4 v[12:13], v[32:35], off offset:-2048
	s_waitcnt vmcnt(7)
	v_pk_mul_f32 v[36:37], v[36:37], v[14:15] op_sel_hi:[1,0]
	v_pk_mul_f32 v[38:39], v[38:39], v[14:15] op_sel_hi:[1,0]
	v_pk_mul_f32 v[36:37], v[36:37], v[68:69]
	v_pk_mul_f32 v[38:39], v[38:39], v[70:71]
	global_store_dwordx4 v[12:13], v[36:39], off offset:-1024
	s_waitcnt vmcnt(7)
	v_pk_mul_f32 v[40:41], v[40:41], v[14:15] op_sel_hi:[1,0]
	v_pk_mul_f32 v[42:43], v[42:43], v[14:15] op_sel_hi:[1,0]
	v_pk_mul_f32 v[40:41], v[40:41], v[72:73]
	v_pk_mul_f32 v[42:43], v[42:43], v[74:75]
	global_store_dwordx4 v[12:13], v[40:43], off
	s_waitcnt vmcnt(7)
	v_pk_mul_f32 v[44:45], v[44:45], v[14:15] op_sel_hi:[1,0]
	v_pk_mul_f32 v[46:47], v[46:47], v[14:15] op_sel_hi:[1,0]
	v_pk_mul_f32 v[44:45], v[44:45], v[76:77]
	v_pk_mul_f32 v[46:47], v[46:47], v[78:79]
	global_store_dwordx4 v[12:13], v[44:47], off offset:1024
	s_waitcnt vmcnt(7)
	v_pk_mul_f32 v[48:49], v[48:49], v[14:15] op_sel_hi:[1,0]
	v_pk_mul_f32 v[50:51], v[50:51], v[14:15] op_sel_hi:[1,0]
	v_pk_mul_f32 v[48:49], v[48:49], v[80:81]
	v_pk_mul_f32 v[50:51], v[50:51], v[82:83]
	global_store_dwordx4 v[12:13], v[48:51], off offset:2048
	s_waitcnt vmcnt(7)
	v_pk_mul_f32 v[52:53], v[52:53], v[14:15] op_sel_hi:[1,0]
	v_pk_mul_f32 v[54:55], v[54:55], v[14:15] op_sel_hi:[1,0]
	v_pk_mul_f32 v[52:53], v[52:53], v[84:85]
	v_pk_mul_f32 v[54:55], v[54:55], v[86:87]
	global_store_dwordx4 v[12:13], v[52:55], off offset:3072
	v_lshl_add_u64 v[12:13], v[12:13], 0, s[26:27]
	s_add_i32 s0, s0, s70
	s_cmpk_lt_i32 s0, 0x4000
	s_cbranch_scc1 .LBB0_644

; __device__ __forceinline__ float bflo(unsigned w) { return __uint_as_float(w << 16); }
; __device__ __forceinline__ float bfhi(unsigned w) { return __uint_as_float(w & 0xffff0000u); }
; __device__ __forceinline__ void pool_prep(const bf16_t* U, bf16_t* PP, const int tid) {
;     ...
;         for (int d = 1; d < cnt; ++d) { const u32x4 q = *(const u32x4*)(U + (size_t)(row - d) * 1024 + ch);
;             s[0] += bflo(q.x); s[1] += bfhi(q.x); s[2] += bflo(q.y); s[3] += bfhi(q.y); s[4] += bflo(q.z); s[5] += bfhi(q.z); s[6] += bflo(q.w); s[7] += bfhi(q.w); }
.Lpp_batch:
	s_mov_b64 s[14:15], exec
	s_movk_i32 s0, 0xe800
	s_mov_b32 s1, -1
	global_load_dwordx4 v[34:37], v[22:23], off
	v_cmp_lt_u32_e32 vcc, 1, v26
	s_and_b64 exec, s[14:15], vcc
	s_cbranch_execz .Lpp_issued
	global_load_dwordx4 v[38:41], v[22:23], off offset:-2048
	v_cmp_lt_u32_e32 vcc, 2, v26
	s_and_b64 exec, s[14:15], vcc
	s_cbranch_execz .Lpp_issued
	global_load_dwordx4 v[42:45], v[22:23], off offset:-4096
	v_cmp_lt_u32_e32 vcc, 3, v26
	s_and_b64 exec, s[14:15], vcc
	s_cbranch_execz .Lpp_issued
	v_lshl_add_u64 v[22:23], v[22:23], 0, s[0:1]
	global_load_dwordx4 v[46:49], v[22:23], off
	v_cmp_lt_u32_e32 vcc, 4, v26
	s_and_b64 exec, s[14:15], vcc
	s_cbranch_execz .Lpp_issued
	global_load_dwordx4 v[50:53], v[22:23], off offset:-2048
	v_cmp_lt_u32_e32 vcc, 5, v26
	s_and_b64 exec, s[14:15], vcc
	s_cbranch_execz .Lpp_issued
	global_load_dwordx4 v[54:57], v[22:23], off offset:-4096
	v_cmp_lt_u32_e32 vcc, 6, v26
	s_and_b64 exec, s[14:15], vcc
	s_cbranch_execz .Lpp_issued
	v_lshl_add_u64 v[22:23], v[22:23], 0, s[0:1]
	global_load_dwordx4 v[58:61], v[22:23], off
	v_cmp_lt_u32_e32 vcc, 7, v26
	s_and_b64 exec, s[14:15], vcc
	s_cbranch_execz .Lpp_issued
	global_load_dwordx4 v[62:65], v[22:23], off offset:-2048
	v_cmp_lt_u32_e32 vcc, 8, v26
	s_and_b64 exec, s[14:15], vcc
	s_cbranch_execz .Lpp_issued
	global_load_dwordx4 v[66:69], v[22:23], off offset:-4096
	v_cmp_lt_u32_e32 vcc, 9, v26
	s_and_b64 exec, s[14:15], vcc
	s_cbranch_execz .Lpp_issued
	v_lshl_add_u64 v[22:23], v[22:23], 0, s[0:1]
	global_load_dwordx4 v[70:73], v[22:23], off
	v_cmp_lt_u32_e32 vcc, 10, v26
	s_and_b64 exec, s[14:15], vcc
	s_cbranch_execz .Lpp_issued
	global_load_dwordx4 v[74:77], v[22:23], off offset:-2048
	v_cmp_lt_u32_e32 vcc, 11, v26
	s_and_b64 exec, s[14:15], vcc
	s_cbranch_execz .Lpp_issued
	global_load_dwordx4 v[78:81], v[22:23], off offset:-4096
	v_cmp_lt_u32_e32 vcc, 12, v26
	s_and_b64 exec, s[14:15], vcc
	s_cbranch_execz .Lpp_issued
	v_lshl_add_u64 v[22:23], v[22:23], 0, s[0:1]
	global_load_dwordx4 v[82:85], v[22:23], off
	v_cmp_lt_u32_e32 vcc, 13, v26
	s_and_b64 exec, s[14:15], vcc
	s_cbranch_execz .Lpp_issued
	global_load_dwordx4 v[86:89], v[22:23], off offset:-2048
	v_cmp_lt_u32_e32 vcc, 14, v26
	s_and_b64 exec, s[14:15], vcc
	s_cbranch_execz .Lpp_issued
	global_load_dwordx4 v[90:93], v[22:23], off offset:-4096
.Lpp_issued:
	s_mov_b64 exec, s[14:15]
	s_waitcnt vmcnt(0)
	v_lshlrev_b32_e32 v32, 16, v34
	v_and_b32_e32 v33, 0xffff0000, v34
	v_lshlrev_b32_e32 v28, 16, v35
	v_and_b32_e32 v29, 0xffff0000, v35
	v_pk_add_f32 v[16:17], v[16:17], v[32:33]
	v_pk_add_f32 v[12:13], v[12:13], v[28:29]
	v_lshlrev_b32_e32 v28, 16, v36
	v_and_b32_e32 v29, 0xffff0000, v36
	v_lshlrev_b32_e32 v30, 16, v37
	v_and_b32_e32 v31, 0xffff0000, v37
	v_pk_add_f32 v[18:19], v[18:19], v[28:29]
	v_pk_add_f32 v[20:21], v[20:21], v[30:31]
	v_cmp_lt_u32_e32 vcc, 1, v26
	s_and_b64 exec, s[14:15], vcc
	s_cbranch_execz .Lpp_done
	v_lshlrev_b32_e32 v32, 16, v38
	v_and_b32_e32 v33, 0xffff0000, v38
	v_lshlrev_b32_e32 v28, 16, v39
	v_and_b32_e32 v29, 0xffff0000, v39
	v_pk_add_f32 v[16:17], v[16:17], v[32:33]
	v_pk_add_f32 v[12:13], v[12:13], v[28:29]
	v_lshlrev_b32_e32 v28, 16, v40
	v_and_b32_e32 v29, 0xffff0000, v40
	v_lshlrev_b32_e32 v30, 16, v41
	v_and_b32_e32 v31, 0xffff0000, v41
	v_pk_add_f32 v[18:19], v[18:19], v[28:29]
	v_pk_add_f32 v[20:21], v[20:21], v[30:31]
	v_cmp_lt_u32_e32 vcc, 2, v26
	s_and_b64 exec, s[14:15], vcc
	s_cbranch_execz .Lpp_done
	v_lshlrev_b32_e32 v32, 16, v42
	v_and_b32_e32 v33, 0xffff0000, v42
	v_lshlrev_b32_e32 v28, 16, v43
	v_and_b32_e32 v29, 0xffff0000, v43
	v_pk_add_f32 v[16:17], v[16:17], v[32:33]
	v_pk_add_f32 v[12:13], v[12:13], v[28:29]
	v_lshlrev_b32_e32 v28, 16, v44
	v_and_b32_e32 v29, 0xffff0000, v44
	v_lshlrev_b32_e32 v30, 16, v45
	v_and_b32_e32 v31, 0xffff0000, v45
	v_pk_add_f32 v[18:19], v[18:19], v[28:29]
	v_pk_add_f32 v[20:21], v[20:21], v[30:31]
	v_cmp_lt_u32_e32 vcc, 3, v26
	s_and_b64 exec, s[14:15], vcc
	s_cbranch_execz .Lpp_done
	v_lshlrev_b32_e32 v32, 16, v46
	v_and_b32_e32 v33, 0xffff0000, v46
	v_lshlrev_b32_e32 v28, 16, v47
	v_and_b32_e32 v29, 0xffff0000, v47
	v_pk_add_f32 v[16:17], v[16:17], v[32:33]
	v_pk_add_f32 v[12:13], v[12:13], v[28:29]
	v_lshlrev_b32_e32 v28, 16, v48
	v_and_b32_e32 v29, 0xffff0000, v48
	v_lshlrev_b32_e32 v30, 16, v49
	v_and_b32_e32 v31, 0xffff0000, v49
	v_pk_add_f32 v[18:19], v[18:19], v[28:29]
	v_pk_add_f32 v[20:21], v[20:21], v[30:31]
	v_cmp_lt_u32_e32 vcc, 4, v26
	s_and_b64 exec, s[14:15], vcc
	s_cbranch_execz .Lpp_done
	v_lshlrev_b32_e32 v32, 16, v50
	v_and_b32_e32 v33, 0xffff0000, v50
	v_lshlrev_b32_e32 v28, 16, v51
	v_and_b32_e32 v29, 0xffff0000, v51
	v_pk_add_f32 v[16:17], v[16:17], v[32:33]
	v_pk_add_f32 v[12:13], v[12:13], v[28:29]
	v_lshlrev_b32_e32 v28, 16, v52
	v_and_b32_e32 v29, 0xffff0000, v52
	v_lshlrev_b32_e32 v30, 16, v53
	v_and_b32_e32 v31, 0xffff0000, v53
	v_pk_add_f32 v[18:19], v[18:19], v[28:29]
	v_pk_add_f32 v[20:21], v[20:21], v[30:31]
	v_cmp_lt_u32_e32 vcc, 5, v26
	s_and_b64 exec, s[14:15], vcc
	s_cbranch_execz .Lpp_done
; __device__ __forceinline__ float bflo(unsigned w) { return __uint_as_float(w << 16); }
; __device__ __forceinline__ float bfhi(unsigned w) { return __uint_as_float(w & 0xffff0000u); }
; __device__ __forceinline__ void pool_prep(const bf16_t* U, bf16_t* PP, const int tid) {
;     ...
;         for (int d = 1; d < cnt; ++d) { const u32x4 q = *(const u32x4*)(U + (size_t)(row - d) * 1024 + ch);
;             s[0] += bflo(q.x); s[1] += bfhi(q.x); s[2] += bflo(q.y); s[3] += bfhi(q.y); s[4] += bflo(q.z); s[5] += bfhi(q.z); s[6] += bflo(q.w); s[7] += bfhi(q.w); }
	v_lshlrev_b32_e32 v32, 16, v54
	v_and_b32_e32 v33, 0xffff0000, v54
	v_lshlrev_b32_e32 v28, 16, v55
	v_and_b32_e32 v29, 0xffff0000, v55
	v_pk_add_f32 v[16:17], v[16:17], v[32:33]
	v_pk_add_f32 v[12:13], v[12:13], v[28:29]
	v_lshlrev_b32_e32 v28, 16, v56
	v_and_b32_e32 v29, 0xffff0000, v56
	v_lshlrev_b32_e32 v30, 16, v57
	v_and_b32_e32 v31, 0xffff0000, v57
	v_pk_add_f32 v[18:19], v[18:19], v[28:29]
	v_pk_add_f32 v[20:21], v[20:21], v[30:31]
	v_cmp_lt_u32_e32 vcc, 6, v26
	s_and_b64 exec, s[14:15], vcc
	s_cbranch_execz .Lpp_done
	v_lshlrev_b32_e32 v32, 16, v58
	v_and_b32_e32 v33, 0xffff0000, v58
	v_lshlrev_b32_e32 v28, 16, v59
	v_and_b32_e32 v29, 0xffff0000, v59
	v_pk_add_f32 v[16:17], v[16:17], v[32:33]
	v_pk_add_f32 v[12:13], v[12:13], v[28:29]
	v_lshlrev_b32_e32 v28, 16, v60
	v_and_b32_e32 v29, 0xffff0000, v60
	v_lshlrev_b32_e32 v30, 16, v61
	v_and_b32_e32 v31, 0xffff0000, v61
	v_pk_add_f32 v[18:19], v[18:19], v[28:29]
	v_pk_add_f32 v[20:21], v[20:21], v[30:31]
	v_cmp_lt_u32_e32 vcc, 7, v26
	s_and_b64 exec, s[14:15], vcc
	s_cbranch_execz .Lpp_done
	v_lshlrev_b32_e32 v32, 16, v62
	v_and_b32_e32 v33, 0xffff0000, v62
	v_lshlrev_b32_e32 v28, 16, v63
	v_and_b32_e32 v29, 0xffff0000, v63
	v_pk_add_f32 v[16:17], v[16:17], v[32:33]
	v_pk_add_f32 v[12:13], v[12:13], v[28:29]
	v_lshlrev_b32_e32 v28, 16, v64
	v_and_b32_e32 v29, 0xffff0000, v64
	v_lshlrev_b32_e32 v30, 16, v65
	v_and_b32_e32 v31, 0xffff0000, v65
	v_pk_add_f32 v[18:19], v[18:19], v[28:29]
	v_pk_add_f32 v[20:21], v[20:21], v[30:31]
	v_cmp_lt_u32_e32 vcc, 8, v26
	s_and_b64 exec, s[14:15], vcc
	s_cbranch_execz .Lpp_done
	v_lshlrev_b32_e32 v32, 16, v66
	v_and_b32_e32 v33, 0xffff0000, v66
	v_lshlrev_b32_e32 v28, 16, v67
	v_and_b32_e32 v29, 0xffff0000, v67
	v_pk_add_f32 v[16:17], v[16:17], v[32:33]
	v_pk_add_f32 v[12:13], v[12:13], v[28:29]
	v_lshlrev_b32_e32 v28, 16, v68
	v_and_b32_e32 v29, 0xffff0000, v68
	v_lshlrev_b32_e32 v30, 16, v69
	v_and_b32_e32 v31, 0xffff0000, v69
	v_pk_add_f32 v[18:19], v[18:19], v[28:29]
	v_pk_add_f32 v[20:21], v[20:21], v[30:31]
	v_cmp_lt_u32_e32 vcc, 9, v26
	s_and_b64 exec, s[14:15], vcc
	s_cbranch_execz .Lpp_done
	v_lshlrev_b32_e32 v32, 16, v70
	v_and_b32_e32 v33, 0xffff0000, v70
	v_lshlrev_b32_e32 v28, 16, v71
	v_and_b32_e32 v29, 0xffff0000, v71
	v_pk_add_f32 v[16:17], v[16:17], v[32:33]
	v_pk_add_f32 v[12:13], v[12:13], v[28:29]
	v_lshlrev_b32_e32 v28, 16, v72
	v_and_b32_e32 v29, 0xffff0000, v72
	v_lshlrev_b32_e32 v30, 16, v73
	v_and_b32_e32 v31, 0xffff0000, v73
	v_pk_add_f32 v[18:19], v[18:19], v[28:29]
	v_pk_add_f32 v[20:21], v[20:21], v[30:31]
	v_cmp_lt_u32_e32 vcc, 10, v26
	s_and_b64 exec, s[14:15], vcc
	s_cbranch_execz .Lpp_done
	v_lshlrev_b32_e32 v32, 16, v74
	v_and_b32_e32 v33, 0xffff0000, v74
	v_lshlrev_b32_e32 v28, 16, v75
	v_and_b32_e32 v29, 0xffff0000, v75
	v_pk_add_f32 v[16:17], v[16:17], v[32:33]
	v_pk_add_f32 v[12:13], v[12:13], v[28:29]
	v_lshlrev_b32_e32 v28, 16, v76
	v_and_b32_e32 v29, 0xffff0000, v76
	v_lshlrev_b32_e32 v30, 16, v77
	v_and_b32_e32 v31, 0xffff0000, v77
	v_pk_add_f32 v[18:19], v[18:19], v[28:29]
	v_pk_add_f32 v[20:21], v[20:21], v[30:31]
	v_cmp_lt_u32_e32 vcc, 11, v26
	s_and_b64 exec, s[14:15], vcc
	s_cbranch_execz .Lpp_done
	v_lshlrev_b32_e32 v32, 16, v78
	v_and_b32_e32 v33, 0xffff0000, v78
	v_lshlrev_b32_e32 v28, 16, v79
	v_and_b32_e32 v29, 0xffff0000, v79
	v_pk_add_f32 v[16:17], v[16:17], v[32:33]
	v_pk_add_f32 v[12:13], v[12:13], v[28:29]
	v_lshlrev_b32_e32 v28, 16, v80
	v_and_b32_e32 v29, 0xffff0000, v80
	v_lshlrev_b32_e32 v30, 16, v81
	v_and_b32_e32 v31, 0xffff0000, v81
	v_pk_add_f32 v[18:19], v[18:19], v[28:29]
	v_pk_add_f32 v[20:21], v[20:21], v[30:31]
	v_cmp_lt_u32_e32 vcc, 12, v26
	s_and_b64 exec, s[14:15], vcc
	s_cbranch_execz .Lpp_done
	v_lshlrev_b32_e32 v32, 16, v82
	v_and_b32_e32 v33, 0xffff0000, v82
	v_lshlrev_b32_e32 v28, 16, v83
	v_and_b32_e32 v29, 0xffff0000, v83
	v_pk_add_f32 v[16:17], v[16:17], v[32:33]
	v_pk_add_f32 v[12:13], v[12:13], v[28:29]
	v_lshlrev_b32_e32 v28, 16, v84
	v_and_b32_e32 v29, 0xffff0000, v84
	v_lshlrev_b32_e32 v30, 16, v85
	v_and_b32_e32 v31, 0xffff0000, v85
	v_pk_add_f32 v[18:19], v[18:19], v[28:29]
	v_pk_add_f32 v[20:21], v[20:21], v[30:31]
	v_cmp_lt_u32_e32 vcc, 13, v26
	s_and_b64 exec, s[14:15], vcc
	s_cbranch_execz .Lpp_done
	v_lshlrev_b32_e32 v32, 16, v86
	v_and_b32_e32 v33, 0xffff0000, v86
	v_lshlrev_b32_e32 v28, 16, v87
	v_and_b32_e32 v29, 0xffff0000, v87
	v_pk_add_f32 v[16:17], v[16:17], v[32:33]
	v_pk_add_f32 v[12:13], v[12:13], v[28:29]
	v_lshlrev_b32_e32 v28, 16, v88
	v_and_b32_e32 v29, 0xffff0000, v88
	v_lshlrev_b32_e32 v30, 16, v89
	v_and_b32_e32 v31, 0xffff0000, v89
	v_pk_add_f32 v[18:19], v[18:19], v[28:29]
	v_pk_add_f32 v[20:21], v[20:21], v[30:31]
	v_cmp_lt_u32_e32 vcc, 14, v26
	s_and_b64 exec, s[14:15], vcc
	s_cbranch_execz .Lpp_done
	v_lshlrev_b32_e32 v32, 16, v90
	v_and_b32_e32 v33, 0xffff0000, v90
	v_lshlrev_b32_e32 v28, 16, v91
	v_and_b32_e32 v29, 0xffff0000, v91
	v_pk_add_f32 v[16:17], v[16:17], v[32:33]
	v_pk_add_f32 v[12:13], v[12:13], v[28:29]
	v_lshlrev_b32_e32 v28, 16, v92
	v_and_b32_e32 v29, 0xffff0000, v92
	v_lshlrev_b32_e32 v30, 16, v93
	v_and_b32_e32 v31, 0xffff0000, v93
	v_pk_add_f32 v[18:19], v[18:19], v[28:29]
	v_pk_add_f32 v[20:21], v[20:21], v[30:31]
.Lpp_done:
	s_branch .LBB0_1298

; __device__ __forceinline__ unsigned cvt_pk_bf16(float lo, float hi) { f32x2 v = {lo, hi}; bf16x2_t b = __builtin_convertvector(v, bf16x2_t); return __builtin_bit_cast(unsigned, b); }
; __device__ __forceinline__ void xb_rows(const float* X, bf16_t* out, float* ssq, int nrows, int gw, int ngw, int lane) {
;     for (int row = gw; row < nrows; row += ngw) {
;         const f32x4* xr = (const f32x4*)(X + (size_t)row * DM) + lane; float ss = 0.f;
; #pragma unroll
;         for (int j = 0; j < 8; ++j) { const f32x4 v = xr[64 * j]; ss += (v[0] * v[0] + v[1] * v[1]) + (v[2] * v[2] + v[3] * v[3]);
;             u32x2 w; w.x = cvt_pk_bf16(v[0], v[1]); w.y = cvt_pk_bf16(v[2], v[3]); ((u32x2*)(out + (size_t)row * DM))[lane + 64 * j] = w; }
;         ss = wave_sum(ss);
;         if (lane == 0) ssq[row] = ss;
;     }
.LBB0_1453:
	global_load_dwordx4 v[84:87], v[6:7], off offset:-4096
	global_load_dwordx4 v[88:91], v[6:7], off offset:-3072
	global_load_dwordx4 v[92:95], v[6:7], off offset:-2048
	global_load_dwordx4 v[96:99], v[6:7], off offset:-1024
	global_load_dwordx4 v[100:103], v[6:7], off
	global_load_dwordx4 v[104:107], v[6:7], off offset:1024
	global_load_dwordx4 v[108:111], v[6:7], off offset:2048
	global_load_dwordx4 v[112:115], v[6:7], off offset:3072
	s_mov_b32 s2, 0x11e00000
	v_lshl_add_u64 v[8:9], s[30:31], 0, v[4:5]
	s_waitcnt lgkmcnt(0)
	v_add_co_u32_e32 v8, vcc, s2, v8
	s_nop 1
	v_addc_co_u32_e32 v9, vcc, 0, v9, vcc
	s_waitcnt vmcnt(7)
	v_mul_f32_e32 v20, v85, v85
	v_mul_f32_e32 v22, v87, v87
	v_fmac_f32_e32 v20, v84, v84
	v_fmac_f32_e32 v22, v86, v86
	v_add_f32_e32 v20, v20, v22
	v_cvt_pk_bf16_f32 v16, v84, v85
	v_cvt_pk_bf16_f32 v17, v86, v87
	global_store_dwordx2 v[8:9], v[16:17], off
	s_waitcnt vmcnt(7)
	v_mul_f32_e32 v21, v89, v89
	v_mul_f32_e32 v22, v91, v91
	v_fmac_f32_e32 v21, v88, v88
	v_fmac_f32_e32 v22, v90, v90
	v_add_f32_e32 v21, v21, v22
	v_add_f32_e32 v20, v20, v21
	v_cvt_pk_bf16_f32 v16, v88, v89
	v_cvt_pk_bf16_f32 v17, v90, v91
	global_store_dwordx2 v[8:9], v[16:17], off offset:512
	s_waitcnt vmcnt(7)
	v_mul_f32_e32 v21, v93, v93
	v_mul_f32_e32 v22, v95, v95
	v_fmac_f32_e32 v21, v92, v92
	v_fmac_f32_e32 v22, v94, v94
	v_add_f32_e32 v21, v21, v22
	v_add_f32_e32 v20, v20, v21
	v_cvt_pk_bf16_f32 v16, v92, v93
	v_cvt_pk_bf16_f32 v17, v94, v95
	global_store_dwordx2 v[8:9], v[16:17], off offset:1024
	s_waitcnt vmcnt(7)
	v_mul_f32_e32 v21, v97, v97
	v_mul_f32_e32 v22, v99, v99
	v_fmac_f32_e32 v21, v96, v96
	v_fmac_f32_e32 v22, v98, v98
	v_add_f32_e32 v21, v21, v22
	v_add_f32_e32 v20, v20, v21
	v_cvt_pk_bf16_f32 v16, v96, v97
	v_cvt_pk_bf16_f32 v17, v98, v99
	global_store_dwordx2 v[8:9], v[16:17], off offset:1536
	s_waitcnt vmcnt(7)
	v_mul_f32_e32 v21, v101, v101
	v_mul_f32_e32 v22, v103, v103
	v_fmac_f32_e32 v21, v100, v100
	v_fmac_f32_e32 v22, v102, v102
	v_add_f32_e32 v21, v21, v22
	v_add_f32_e32 v20, v20, v21
	v_cvt_pk_bf16_f32 v16, v100, v101
	v_cvt_pk_bf16_f32 v17, v102, v103
	global_store_dwordx2 v[8:9], v[16:17], off offset:2048
	s_waitcnt vmcnt(7)
	v_mul_f32_e32 v21, v105, v105
	v_mul_f32_e32 v22, v107, v107
	v_fmac_f32_e32 v21, v104, v104
	v_fmac_f32_e32 v22, v106, v106
	v_add_f32_e32 v21, v21, v22
	v_add_f32_e32 v20, v20, v21
	v_cvt_pk_bf16_f32 v16, v104, v105
	v_cvt_pk_bf16_f32 v17, v106, v107
	global_store_dwordx2 v[8:9], v[16:17], off offset:2560
	s_waitcnt vmcnt(7)
	v_mul_f32_e32 v21, v109, v109
	v_mul_f32_e32 v22, v111, v111
	v_fmac_f32_e32 v21, v108, v108
	v_fmac_f32_e32 v22, v110, v110
	v_add_f32_e32 v21, v21, v22
	v_add_f32_e32 v20, v20, v21
	v_cvt_pk_bf16_f32 v16, v108, v109
	v_cvt_pk_bf16_f32 v17, v110, v111
	global_store_dwordx2 v[8:9], v[16:17], off offset:3072
	s_waitcnt vmcnt(7)
	v_mul_f32_e32 v21, v113, v113
	v_mul_f32_e32 v22, v115, v115
	v_fmac_f32_e32 v21, v112, v112
	v_fmac_f32_e32 v22, v114, v114
	v_add_f32_e32 v21, v21, v22
	v_add_f32_e32 v20, v20, v21
	v_cvt_pk_bf16_f32 v16, v112, v113
	v_cvt_pk_bf16_f32 v17, v114, v115
	global_store_dwordx2 v[8:9], v[16:17], off offset:3584
	ds_bpermute_b32 v8, v10, v20
	s_waitcnt lgkmcnt(0)
	v_add_f32_e32 v8, v20, v8
	ds_bpermute_b32 v9, v11, v8
	s_waitcnt lgkmcnt(0)
	v_add_f32_e32 v8, v8, v9
	ds_bpermute_b32 v9, v12, v8
	s_waitcnt lgkmcnt(0)
	v_add_f32_e32 v8, v8, v9
	ds_bpermute_b32 v9, v13, v8
	s_waitcnt lgkmcnt(0)
	v_add_f32_e32 v8, v8, v9
	ds_bpermute_b32 v9, v14, v8
	s_waitcnt lgkmcnt(0)
	v_add_f32_e32 v8, v8, v9
	ds_bpermute_b32 v9, v15, v8
	s_and_saveexec_b64 s[2:3], s[6:7]
	s_cbranch_execz .LBB0_1452
	s_add_u32 s10, s30, s0
	s_waitcnt lgkmcnt(0)
	v_add_f32_e32 v8, v8, v9
	s_addc_u32 s11, s31, s1
	global_store_dword v0, v8, s[10:11]
	s_branch .LBB0_1452
